# P4 pool-difference units: 32 cache-warming loads of the unit's rows issued at unit start (the per-token load->wait chain then hits L2)
# speedup vs baseline: 1.0002x; 1.0002x over previous
; __host__ __device__ __forceinline__ size_t blk_off(int r, int k, int KT) { return ((size_t)((r >> 8) * KT + (k >> 6)) * 256 + (size_t)(r & 255)) * 64 + (size_t)(k & 63); }
; __device__ __forceinline__ unsigned cvt_pk_bf16(float lo, float hi) { unsigned r; asm volatile("v_cvt_pk_bf16_f32 %0, %1, %2" : "=v"(r) : "v"(lo), "v"(hi)); return r; }
; template <int W>
; __device__ __forceinline__ void pool_d_seg(const float* ub, bf16_t* db, int t0, int cq) {
;     f32x4 ring[W]; f32x4 sum = (f32x4){0.f, 0.f, 0.f, 0.f};
;     const int tp0 = t0 & 2047;
; #pragma unroll
;     for (int i = 0; i < W; ++i) { ring[i] = (tp0 - W + i >= 0) ? *(const f32x4*)(ub + (size_t)(t0 - W + i) * DPOOL + 4 * cq) : (f32x4){0.f, 0.f, 0.f, 0.f}; sum += ring[i]; }
;     for (int c0 = 0; c0 < 32; c0 += W) {
; #pragma unroll
;         for (int i = 0; i < W; ++i) {
;             const int t = t0 + c0 + i; const f32x4 x = *(const f32x4*)(ub + (size_t)t * DPOOL + 4 * cq);
;             sum = sum + x - ring[i]; ring[i] = x;
;             const int tp = tp0 + c0 + i; const float inv = 1.0f / (float)(tp + 1 < W ? tp + 1 : W);
;             const f32x4 d = sum * inv - x;
;             u32x2 w; w.x = cvt_pk_bf16(d.x, d.y); w.y = cvt_pk_bf16(d.z, d.w);
;             *(u32x2*)(db + (size_t)(cq >> 7) * M * 512 + blk_off(t, (4 * cq) & 511, KTP)) = w;
;         }
;     }
; }
; __device__ __forceinline__ void pool_d_unit(Frame& F, int seg) {
;     const float* ub = (const float*)(F.ws + WS_U); bf16_t* db = (bf16_t*)(F.ws + WS_DPOOL);
;     const int cq = F.tid, gi = cq >> 7, t0 = seg * 32;
;     if (gi == 0) pool_d_seg<2>(ub, db, t0, cq); else if (gi == 1) pool_d_seg<4>(ub, db, t0, cq); else if (gi == 2) pool_d_seg<8>(ub, db, t0, cq); else pool_d_seg<16>(ub, db, t0, cq);
.LBB0_2435:
	s_lshl_b32 s26, s67, 5
	s_mov_b32 s98, s26
	s_mov_b32 s99, 0
	s_lshl_b64 s[98:99], s[98:99], 13
	v_lshl_add_u64 v[248:249], v[72:73], 0, s[98:99]
	v_mov_b32_e32 v250, 0x2000
	v_mov_b32_e32 v251, 0
	global_load_dwordx4 v[252:255], v[248:249], off
	v_lshl_add_u64 v[248:249], v[248:249], 0, v[250:251]
	global_load_dwordx4 v[252:255], v[248:249], off
	v_lshl_add_u64 v[248:249], v[248:249], 0, v[250:251]
	global_load_dwordx4 v[252:255], v[248:249], off
	v_lshl_add_u64 v[248:249], v[248:249], 0, v[250:251]
	global_load_dwordx4 v[252:255], v[248:249], off
	v_lshl_add_u64 v[248:249], v[248:249], 0, v[250:251]
	global_load_dwordx4 v[252:255], v[248:249], off
	v_lshl_add_u64 v[248:249], v[248:249], 0, v[250:251]
	global_load_dwordx4 v[252:255], v[248:249], off
	v_lshl_add_u64 v[248:249], v[248:249], 0, v[250:251]
	global_load_dwordx4 v[252:255], v[248:249], off
	v_lshl_add_u64 v[248:249], v[248:249], 0, v[250:251]
	global_load_dwordx4 v[252:255], v[248:249], off
	v_lshl_add_u64 v[248:249], v[248:249], 0, v[250:251]
	global_load_dwordx4 v[252:255], v[248:249], off
	v_lshl_add_u64 v[248:249], v[248:249], 0, v[250:251]
	global_load_dwordx4 v[252:255], v[248:249], off
	v_lshl_add_u64 v[248:249], v[248:249], 0, v[250:251]
	global_load_dwordx4 v[252:255], v[248:249], off
	v_lshl_add_u64 v[248:249], v[248:249], 0, v[250:251]
	global_load_dwordx4 v[252:255], v[248:249], off
	v_lshl_add_u64 v[248:249], v[248:249], 0, v[250:251]
	global_load_dwordx4 v[252:255], v[248:249], off
	v_lshl_add_u64 v[248:249], v[248:249], 0, v[250:251]
	global_load_dwordx4 v[252:255], v[248:249], off
	v_lshl_add_u64 v[248:249], v[248:249], 0, v[250:251]
	global_load_dwordx4 v[252:255], v[248:249], off
	v_lshl_add_u64 v[248:249], v[248:249], 0, v[250:251]
	global_load_dwordx4 v[252:255], v[248:249], off
	v_lshl_add_u64 v[248:249], v[248:249], 0, v[250:251]
	global_load_dwordx4 v[252:255], v[248:249], off
	v_lshl_add_u64 v[248:249], v[248:249], 0, v[250:251]
	global_load_dwordx4 v[252:255], v[248:249], off
	v_lshl_add_u64 v[248:249], v[248:249], 0, v[250:251]
	global_load_dwordx4 v[252:255], v[248:249], off
	v_lshl_add_u64 v[248:249], v[248:249], 0, v[250:251]
	global_load_dwordx4 v[252:255], v[248:249], off
	v_lshl_add_u64 v[248:249], v[248:249], 0, v[250:251]
	global_load_dwordx4 v[252:255], v[248:249], off
	v_lshl_add_u64 v[248:249], v[248:249], 0, v[250:251]
	global_load_dwordx4 v[252:255], v[248:249], off
	v_lshl_add_u64 v[248:249], v[248:249], 0, v[250:251]
	global_load_dwordx4 v[252:255], v[248:249], off
	v_lshl_add_u64 v[248:249], v[248:249], 0, v[250:251]
	global_load_dwordx4 v[252:255], v[248:249], off
	v_lshl_add_u64 v[248:249], v[248:249], 0, v[250:251]
	global_load_dwordx4 v[252:255], v[248:249], off
	v_lshl_add_u64 v[248:249], v[248:249], 0, v[250:251]
	global_load_dwordx4 v[252:255], v[248:249], off
	v_lshl_add_u64 v[248:249], v[248:249], 0, v[250:251]
	global_load_dwordx4 v[252:255], v[248:249], off
	v_lshl_add_u64 v[248:249], v[248:249], 0, v[250:251]
	global_load_dwordx4 v[252:255], v[248:249], off
	v_lshl_add_u64 v[248:249], v[248:249], 0, v[250:251]
	global_load_dwordx4 v[252:255], v[248:249], off
	v_lshl_add_u64 v[248:249], v[248:249], 0, v[250:251]
	global_load_dwordx4 v[252:255], v[248:249], off
	v_lshl_add_u64 v[248:249], v[248:249], 0, v[250:251]
	global_load_dwordx4 v[252:255], v[248:249], off
	v_lshl_add_u64 v[248:249], v[248:249], 0, v[250:251]
	global_load_dwordx4 v[252:255], v[248:249], off
	s_and_b32 s19, s26, 0x7e0
	s_cmp_lg_u32 s19, 0
	s_cselect_b64 s[28:29], -1, 0
	s_and_saveexec_b64 s[0:1], s[46:47]
	s_xor_b64 s[30:31], exec, s[0:1]
	s_cbranch_execz .LBB0_2511
	s_and_b32 s13, s12, 0x7e0
	v_cmp_lt_i32_e32 vcc, 1, v75
	s_mov_b64 s[0:1], 0
	s_mov_b64 s[2:3], 0
	s_and_saveexec_b64 s[4:5], vcc
	s_xor_b64 s[34:35], exec, s[4:5]
	s_cbranch_execz .LBB0_2453
	v_cmp_eq_u32_e32 vcc, 2, v75
	s_mov_b64 s[2:3], -1
	s_and_saveexec_b64 s[36:37], vcc
	s_cbranch_execz .LBB0_2461
	v_cndmask_b32_e64 v2, 0, 1, s[28:29]
	s_waitcnt vmcnt(0)
	v_mov_b32_e32 v28, 0
	v_cmp_ne_u32_e64 s[4:5], 1, v2
	s_andn2_b64 vcc, exec, s[28:29]
	v_mov_b32_e32 v36, 0
	v_mov_b32_e32 v37, 0
	v_mov_b32_e32 v38, 0
	v_mov_b32_e32 v39, 0
	s_cbranch_vccnz .LBB0_2440
	s_ashr_i32 s27, s26, 31
	s_lshl_b64 s[2:3], s[26:27], 13
	v_lshl_add_u64 v[4:5], v[72:73], 0, s[2:3]
	v_add_co_u32_e32 v4, vcc, 0xffff0000, v4
	s_nop 1
	v_addc_co_u32_e32 v5, vcc, -1, v5, vcc
	global_load_dwordx4 v[36:39], v[4:5], off
